# layer-1 w_in bias vector computed in the idle tail of the layer-0 w_out phase instead of after the down projection
# speedup vs baseline: 1.0082x; 1.0082x over previous
.LBB0_612:
	s_mov_b32 s0, 0
	v_readlane_b32 s94, v254, 6
	s_lshl_b32 s95, s94, 3
	s_sub_i32 s95, s90, s95
	s_sub_i32 s96, s70, s94
	s_cmp_lg_u32 s94, 0x60
	s_cbranch_scc1 .Lb1_norot
	s_cmp_lg_u32 s70, 0x100
	s_cbranch_scc1 .Lb1_norot
	s_add_i32 s98, s95, 0x300
	s_add_i32 s95, s95, 0xfffffe00
	s_cmp_lt_i32 s95, 0
	s_cselect_b32 s95, s98, s95

.LBB0_915:
	v_lshl_add_u64 v[0:1], s[8:9], 0, v[76:77]
	v_lshl_add_u64 v[2:3], v[0:1], 0, s[18:19]
	global_load_dwordx4 v[78:81], v[2:3], off offset:16
	v_lshl_add_u64 v[2:3], v[0:1], 0, s[20:21]
	global_load_dwordx4 v[82:85], v[2:3], off offset:16
	global_load_dwordx4 v[94:97], v[66:67], off offset:32
	global_load_dwordx4 v[98:101], v[66:67], off offset:48
	v_lshl_add_u64 v[2:3], v[0:1], 0, s[22:23]
	global_load_dwordx4 v[102:105], v[2:3], off offset:16
	v_lshl_add_u64 v[2:3], v[0:1], 0, s[24:25]
	global_load_dwordx4 v[106:109], v[2:3], off offset:16
	global_load_dwordx4 v[126:129], v[68:69], off offset:48
	global_load_dwordx4 v[138:141], v[68:69], off offset:32
	v_add_co_u32_e32 v2, vcc, 0x1700000, v0
	s_waitcnt vmcnt(6)
	v_lshlrev_b32_e32 v124, 16, v82
	v_addc_co_u32_e32 v3, vcc, 0, v1, vcc
	v_add_co_u32_e32 v0, vcc, s0, v0
	global_load_dwordx4 v[56:59], v[2:3], off
	global_load_dwordx4 v[60:63], v[2:3], off offset:2048
	v_addc_co_u32_e32 v1, vcc, 0, v1, vcc
	global_load_dwordx4 v[40:43], v[0:1], off
	global_load_dwordx4 v[44:47], v[0:1], off offset:2048
	global_load_dwordx4 v[36:39], v[66:67], off offset:16
	global_load_dwordx4 v[52:55], v[66:67], off
	s_waitcnt lgkmcnt(8)
	global_load_dwordx4 v[24:27], v[68:69], off offset:16
	global_load_dwordx4 v[48:51], v[68:69], off
	s_waitcnt lgkmcnt(6)
	global_load_dwordx4 v[20:23], v[70:71], off offset:16
	global_load_dwordx4 v[32:35], v[70:71], off
	global_load_dwordx4 v[142:145], v[70:71], off offset:48
	global_load_dwordx4 v[146:149], v[70:71], off offset:32
	global_load_dwordx4 v[16:19], v[72:73], off offset:16
	global_load_dwordx4 v[28:31], v[72:73], off
	global_load_dwordx4 v[150:153], v[72:73], off offset:48
	global_load_dwordx4 v[154:157], v[72:73], off offset:32
	global_load_dwordx4 v[0:3], v[74:75], off offset:48
	s_waitcnt lgkmcnt(0)
	global_load_dwordx4 v[4:7], v[74:75], off offset:32
	global_load_dwordx4 v[8:11], v[74:75], off offset:16
	global_load_dwordx4 v[12:15], v[74:75], off
	v_and_b32_e32 v125, 0xffff0000, v78
	v_and_b32_e32 v121, 0xffff0000, v79
	v_lshlrev_b32_e32 v120, 16, v83
	v_lshlrev_b32_e32 v122, 16, v78
	v_lshlrev_b32_e32 v118, 16, v79
	v_and_b32_e32 v123, 0xffff0000, v82
	v_and_b32_e32 v119, 0xffff0000, v83
	s_waitcnt vmcnt(25)
	v_pk_mul_f32 v[158:159], v[94:95], v[124:125]
	v_pk_mul_f32 v[160:161], v[96:97], v[120:121]
	v_lshlrev_b32_e32 v114, 16, v80
	v_and_b32_e32 v116, 0xffff0000, v80
	v_lshlrev_b32_e32 v110, 16, v81
	v_lshlrev_b32_e32 v117, 16, v84
	v_and_b32_e32 v115, 0xffff0000, v84
	v_and_b32_e32 v111, 0xffff0000, v85
	s_waitcnt vmcnt(23)
	v_lshlrev_b32_e32 v88, 16, v102
	v_and_b32_e32 v93, 0xffff0000, v102
	v_lshlrev_b32_e32 v86, 16, v103
	v_and_b32_e32 v91, 0xffff0000, v103
	v_lshlrev_b32_e32 v82, 16, v104
	v_and_b32_e32 v84, 0xffff0000, v104
	v_lshlrev_b32_e32 v78, 16, v105
	v_and_b32_e32 v80, 0xffff0000, v105
	s_waitcnt vmcnt(22)
	v_lshlrev_b32_e32 v92, 16, v106
	v_lshlrev_b32_e32 v90, 16, v107
	v_pk_fma_f32 v[102:103], v[94:95], v[122:123], v[158:159] op_sel:[0,0,1] op_sel_hi:[1,1,0]
	v_pk_fma_f32 v[104:105], v[96:97], v[118:119], v[160:161] op_sel:[0,0,1] op_sel_hi:[1,1,0]
	v_and_b32_e32 v112, 0xffff0000, v81
	v_lshlrev_b32_e32 v113, 16, v85
	v_pk_mul_f32 v[162:163], v[98:99], v[114:115]
	v_pk_mul_f32 v[164:165], v[100:101], v[110:111]
	v_and_b32_e32 v89, 0xffff0000, v106
	v_and_b32_e32 v87, 0xffff0000, v107
	v_pk_mul_f32 v[158:159], v[94:95], v[92:93]
	v_pk_add_f32 v[160:161], v[102:103], v[104:105]
	v_pk_mul_f32 v[102:103], v[96:97], v[90:91]
	v_lshlrev_b32_e32 v85, 16, v108
	v_and_b32_e32 v83, 0xffff0000, v108
	v_lshlrev_b32_e32 v81, 16, v109
	v_and_b32_e32 v79, 0xffff0000, v109
	v_pk_fma_f32 v[106:107], v[98:99], v[116:117], v[162:163] op_sel:[1,0,0] op_sel_hi:[0,1,1]
	v_pk_fma_f32 v[108:109], v[100:101], v[112:113], v[164:165] op_sel:[1,0,0] op_sel_hi:[0,1,1]
	v_pk_fma_f32 v[94:95], v[94:95], v[88:89], v[158:159] op_sel:[0,0,1] op_sel_hi:[1,1,0]
	v_pk_fma_f32 v[96:97], v[96:97], v[86:87], v[102:103] op_sel:[0,0,1] op_sel_hi:[1,1,0]
	v_pk_add_f32 v[162:163], v[106:107], v[108:109]
	v_pk_add_f32 v[106:107], v[94:95], v[96:97]
	v_pk_mul_f32 v[94:95], v[98:99], v[82:83]
	v_pk_mul_f32 v[96:97], v[100:101], v[78:79]
	v_pk_fma_f32 v[94:95], v[98:99], v[84:85], v[94:95] op_sel:[1,0,0] op_sel_hi:[0,1,1]
	v_pk_fma_f32 v[96:97], v[100:101], v[80:81], v[96:97] op_sel:[1,0,0] op_sel_hi:[0,1,1]
	v_pk_add_f32 v[108:109], v[94:95], v[96:97]
	s_waitcnt vmcnt(20)
	v_pk_mul_f32 v[94:95], v[138:139], v[124:125]
	v_pk_mul_f32 v[96:97], v[140:141], v[120:121]
	v_pk_fma_f32 v[94:95], v[138:139], v[122:123], v[94:95] op_sel:[0,0,1] op_sel_hi:[1,1,0]
	v_pk_fma_f32 v[96:97], v[140:141], v[118:119], v[96:97] op_sel:[0,0,1] op_sel_hi:[1,1,0]
	s_waitcnt vmcnt(19)
	v_lshlrev_b32_e32 v170, 16, v59
	v_pk_add_f32 v[158:159], v[94:95], v[96:97]
	v_pk_mul_f32 v[94:95], v[126:127], v[114:115]
	v_pk_mul_f32 v[96:97], v[128:129], v[110:111]
	v_pk_fma_f32 v[94:95], v[126:127], v[116:117], v[94:95] op_sel:[1,0,0] op_sel_hi:[0,1,1]
	v_pk_fma_f32 v[96:97], v[128:129], v[112:113], v[96:97] op_sel:[1,0,0] op_sel_hi:[0,1,1]
	v_pk_add_f32 v[164:165], v[94:95], v[96:97]
	v_pk_mul_f32 v[94:95], v[138:139], v[92:93]
	v_pk_mul_f32 v[96:97], v[140:141], v[90:91]
	v_pk_fma_f32 v[94:95], v[138:139], v[88:89], v[94:95] op_sel:[0,0,1] op_sel_hi:[1,1,0]
	v_pk_fma_f32 v[96:97], v[140:141], v[86:87], v[96:97] op_sel:[0,0,1] op_sel_hi:[1,1,0]
	s_waitcnt vmcnt(18)
	v_and_b32_e32 v171, 0xffff0000, v63
	v_pk_add_f32 v[102:103], v[94:95], v[96:97]
	v_pk_mul_f32 v[94:95], v[126:127], v[82:83]
	v_pk_mul_f32 v[96:97], v[128:129], v[78:79]
	v_pk_fma_f32 v[94:95], v[126:127], v[84:85], v[94:95] op_sel:[1,0,0] op_sel_hi:[0,1,1]
	v_pk_fma_f32 v[96:97], v[128:129], v[80:81], v[96:97] op_sel:[1,0,0] op_sel_hi:[0,1,1]
	v_pk_add_f32 v[104:105], v[94:95], v[96:97]
	s_waitcnt vmcnt(8)
	v_pk_mul_f32 v[94:95], v[146:147], v[124:125]
	v_pk_mul_f32 v[96:97], v[148:149], v[120:121]
	v_pk_fma_f32 v[94:95], v[146:147], v[122:123], v[94:95] op_sel:[0,0,1] op_sel_hi:[1,1,0]
	v_pk_fma_f32 v[96:97], v[148:149], v[118:119], v[96:97] op_sel:[0,0,1] op_sel_hi:[1,1,0]
	s_waitcnt vmcnt(5)
	v_pk_mul_f32 v[126:127], v[152:153], v[78:79]
	v_pk_add_f32 v[138:139], v[94:95], v[96:97]
	v_pk_mul_f32 v[94:95], v[142:143], v[114:115]
	v_pk_mul_f32 v[96:97], v[144:145], v[110:111]
	v_pk_fma_f32 v[94:95], v[142:143], v[116:117], v[94:95] op_sel:[1,0,0] op_sel_hi:[0,1,1]
	v_pk_fma_f32 v[96:97], v[144:145], v[112:113], v[96:97] op_sel:[1,0,0] op_sel_hi:[0,1,1]
	v_pk_add_f32 v[140:141], v[94:95], v[96:97]
	v_pk_mul_f32 v[94:95], v[146:147], v[92:93]
	v_pk_mul_f32 v[96:97], v[148:149], v[90:91]
	v_pk_fma_f32 v[94:95], v[146:147], v[88:89], v[94:95] op_sel:[0,0,1] op_sel_hi:[1,1,0]
	v_pk_fma_f32 v[96:97], v[148:149], v[86:87], v[96:97] op_sel:[0,0,1] op_sel_hi:[1,1,0]
	v_pk_fma_f32 v[126:127], v[152:153], v[80:81], v[126:127] op_sel:[1,0,0] op_sel_hi:[0,1,1]
	v_pk_add_f32 v[98:99], v[94:95], v[96:97]
	v_pk_mul_f32 v[94:95], v[142:143], v[82:83]
	v_pk_mul_f32 v[96:97], v[144:145], v[78:79]
	v_pk_fma_f32 v[94:95], v[142:143], v[84:85], v[94:95] op_sel:[1,0,0] op_sel_hi:[0,1,1]
	v_pk_fma_f32 v[96:97], v[144:145], v[80:81], v[96:97] op_sel:[1,0,0] op_sel_hi:[0,1,1]
	v_pk_add_f32 v[100:101], v[94:95], v[96:97]
	s_waitcnt vmcnt(4)
	v_pk_mul_f32 v[94:95], v[154:155], v[124:125]
	v_pk_mul_f32 v[96:97], v[156:157], v[120:121]
	v_pk_fma_f32 v[94:95], v[154:155], v[122:123], v[94:95] op_sel:[0,0,1] op_sel_hi:[1,1,0]
	v_pk_fma_f32 v[96:97], v[156:157], v[118:119], v[96:97] op_sel:[0,0,1] op_sel_hi:[1,1,0]
	v_lshlrev_b32_e32 v144, 16, v56
	v_pk_add_f32 v[128:129], v[94:95], v[96:97]
	v_pk_mul_f32 v[94:95], v[150:151], v[114:115]
	v_pk_mul_f32 v[96:97], v[152:153], v[110:111]
	v_pk_fma_f32 v[94:95], v[150:151], v[116:117], v[94:95] op_sel:[1,0,0] op_sel_hi:[0,1,1]
	v_pk_fma_f32 v[96:97], v[152:153], v[112:113], v[96:97] op_sel:[1,0,0] op_sel_hi:[0,1,1]
	v_pk_add_f32 v[142:143], v[94:95], v[96:97]
	v_pk_mul_f32 v[94:95], v[154:155], v[92:93]
	v_pk_mul_f32 v[96:97], v[156:157], v[90:91]
	v_pk_fma_f32 v[94:95], v[154:155], v[88:89], v[94:95] op_sel:[0,0,1] op_sel_hi:[1,1,0]
	v_pk_fma_f32 v[96:97], v[156:157], v[86:87], v[96:97] op_sel:[0,0,1] op_sel_hi:[1,1,0]
	v_and_b32_e32 v145, 0xffff0000, v60
	v_pk_add_f32 v[94:95], v[94:95], v[96:97]
	v_pk_mul_f32 v[96:97], v[150:151], v[82:83]
	v_and_b32_e32 v154, 0xffff0000, v57
	v_pk_fma_f32 v[96:97], v[150:151], v[84:85], v[96:97] op_sel:[1,0,0] op_sel_hi:[0,1,1]
	v_pk_add_f32 v[96:97], v[96:97], v[126:127]
	v_and_b32_e32 v126, 0xffff0000, v56
	v_lshlrev_b32_e32 v56, 16, v57
	v_and_b32_e32 v57, 0xffff0000, v61
	v_lshlrev_b32_e32 v127, 16, v60
	v_pk_mul_f32 v[146:147], v[52:53], v[144:145]
	v_lshlrev_b32_e32 v155, 16, v61
	v_pk_mul_f32 v[60:61], v[54:55], v[56:57]
	v_pk_fma_f32 v[146:147], v[52:53], v[126:127], v[146:147] op_sel:[1,0,0] op_sel_hi:[0,1,1]
	v_pk_fma_f32 v[60:61], v[54:55], v[154:155], v[60:61] op_sel:[1,0,0] op_sel_hi:[0,1,1]
	v_pk_mul_f32 v[148:149], v[48:49], v[144:145]
	v_pk_add_f32 v[60:61], v[146:147], v[60:61]
	v_pk_mul_f32 v[146:147], v[50:51], v[56:57]
	v_pk_fma_f32 v[148:149], v[48:49], v[126:127], v[148:149] op_sel:[1,0,0] op_sel_hi:[0,1,1]
	v_pk_fma_f32 v[146:147], v[50:51], v[154:155], v[146:147] op_sel:[1,0,0] op_sel_hi:[0,1,1]
	v_lshlrev_b32_e32 v156, 16, v58
	v_and_b32_e32 v157, 0xffff0000, v62
	v_pk_add_f32 v[146:147], v[148:149], v[146:147]
	v_and_b32_e32 v148, 0xffff0000, v58
	v_lshlrev_b32_e32 v149, 16, v62
	v_pk_mul_f32 v[166:167], v[36:37], v[156:157]
	v_and_b32_e32 v168, 0xffff0000, v59
	v_lshlrev_b32_e32 v169, 16, v63
	v_pk_mul_f32 v[58:59], v[38:39], v[170:171]
	v_pk_fma_f32 v[166:167], v[36:37], v[148:149], v[166:167] op_sel:[1,0,0] op_sel_hi:[0,1,1]
	v_pk_fma_f32 v[58:59], v[38:39], v[168:169], v[58:59] op_sel:[1,0,0] op_sel_hi:[0,1,1]
	v_pk_add_f32 v[58:59], v[166:167], v[58:59]
	v_pk_mul_f32 v[150:151], v[32:33], v[144:145]
	v_pk_add_f32 v[58:59], v[60:61], v[58:59]
	v_pk_mul_f32 v[62:63], v[34:35], v[56:57]
	v_pk_add_f32 v[58:59], v[58:59], v[160:161]
	v_pk_fma_f32 v[150:151], v[32:33], v[126:127], v[150:151] op_sel:[1,0,0] op_sel_hi:[0,1,1]
	v_pk_add_f32 v[58:59], v[58:59], v[162:163]
	ds_swizzle_b32 v60, v58 offset:swizzle(SWAP,1)
	ds_swizzle_b32 v61, v59 offset:swizzle(SWAP,1)
	v_pk_fma_f32 v[62:63], v[34:35], v[154:155], v[62:63] op_sel:[1,0,0] op_sel_hi:[0,1,1]
	v_pk_mul_f32 v[152:153], v[28:29], v[144:145]
	v_pk_add_f32 v[62:63], v[150:151], v[62:63]
	v_pk_mul_f32 v[150:151], v[30:31], v[56:57]
	v_pk_fma_f32 v[152:153], v[28:29], v[126:127], v[152:153] op_sel:[1,0,0] op_sel_hi:[0,1,1]
	s_waitcnt lgkmcnt(0)
	v_pk_add_f32 v[58:59], v[58:59], v[60:61]
	v_pk_fma_f32 v[150:151], v[30:31], v[154:155], v[150:151] op_sel:[1,0,0] op_sel_hi:[0,1,1]
	ds_swizzle_b32 v60, v58 offset:swizzle(SWAP,2)
	ds_swizzle_b32 v61, v59 offset:swizzle(SWAP,2)
	v_pk_add_f32 v[150:151], v[152:153], v[150:151]
	s_waitcnt vmcnt(0)
	v_pk_mul_f32 v[152:153], v[14:15], v[56:57]
	v_pk_mul_f32 v[56:57], v[24:25], v[156:157]
	v_pk_mul_f32 v[166:167], v[26:27], v[170:171]
	v_pk_fma_f32 v[56:57], v[24:25], v[148:149], v[56:57] op_sel:[1,0,0] op_sel_hi:[0,1,1]
	v_pk_fma_f32 v[166:167], v[26:27], v[168:169], v[166:167] op_sel:[1,0,0] op_sel_hi:[0,1,1]
	v_pk_add_f32 v[56:57], v[56:57], v[166:167]
	v_pk_mul_f32 v[162:163], v[16:17], v[156:157]
	v_pk_add_f32 v[56:57], v[146:147], v[56:57]
	s_waitcnt lgkmcnt(0)
	v_pk_add_f32 v[58:59], v[58:59], v[60:61]
	v_pk_add_f32 v[56:57], v[56:57], v[158:159]
	v_pk_mul_f32 v[160:161], v[20:21], v[156:157]
	v_pk_add_f32 v[56:57], v[56:57], v[164:165]
	v_pk_fma_f32 v[158:159], v[16:17], v[148:149], v[162:163] op_sel:[1,0,0] op_sel_hi:[0,1,1]
	v_pk_mul_f32 v[162:163], v[22:23], v[170:171]
	ds_swizzle_b32 v60, v58 offset:swizzle(SWAP,4)
	ds_swizzle_b32 v61, v59 offset:swizzle(SWAP,4)
	v_pk_fma_f32 v[160:161], v[20:21], v[148:149], v[160:161] op_sel:[1,0,0] op_sel_hi:[0,1,1]
	ds_swizzle_b32 v146, v56 offset:swizzle(SWAP,1)
	ds_swizzle_b32 v147, v57 offset:swizzle(SWAP,1)
	v_pk_fma_f32 v[162:163], v[22:23], v[168:169], v[162:163] op_sel:[1,0,0] op_sel_hi:[0,1,1]
	v_pk_add_f32 v[160:161], v[160:161], v[162:163]
	s_waitcnt lgkmcnt(2)
	v_pk_add_f32 v[58:59], v[58:59], v[60:61]
	v_pk_add_f32 v[62:63], v[62:63], v[160:161]
	s_waitcnt lgkmcnt(0)
	v_pk_add_f32 v[56:57], v[56:57], v[146:147]
	v_pk_add_f32 v[62:63], v[62:63], v[138:139]
	ds_swizzle_b32 v60, v58 offset:swizzle(SWAP,8)
	v_pk_add_f32 v[62:63], v[62:63], v[140:141]
	ds_swizzle_b32 v138, v62 offset:swizzle(SWAP,1)
	ds_swizzle_b32 v139, v63 offset:swizzle(SWAP,1)
	ds_swizzle_b32 v61, v59 offset:swizzle(SWAP,8)
	ds_swizzle_b32 v146, v56 offset:swizzle(SWAP,2)
	ds_swizzle_b32 v147, v57 offset:swizzle(SWAP,2)
	v_pk_mul_f32 v[144:145], v[12:13], v[144:145]
	s_waitcnt lgkmcnt(3)
	v_pk_add_f32 v[62:63], v[62:63], v[138:139]
	s_waitcnt lgkmcnt(2)
	v_pk_add_f32 v[58:59], v[58:59], v[60:61]
	ds_swizzle_b32 v138, v62 offset:swizzle(SWAP,2)
	s_waitcnt lgkmcnt(1)
	v_pk_add_f32 v[140:141], v[56:57], v[146:147]
	ds_swizzle_b32 v139, v63 offset:swizzle(SWAP,2)
	ds_swizzle_b32 v60, v58 offset:swizzle(SWAP,16)
	ds_swizzle_b32 v61, v59 offset:swizzle(SWAP,16)
	ds_swizzle_b32 v146, v140 offset:swizzle(SWAP,4)
	ds_swizzle_b32 v147, v141 offset:swizzle(SWAP,4)
	s_waitcnt lgkmcnt(4)
	v_pk_add_f32 v[138:139], v[62:63], v[138:139]
	v_pk_mul_f32 v[156:157], v[8:9], v[156:157]
	s_waitcnt lgkmcnt(2)
	v_pk_add_f32 v[56:57], v[58:59], v[60:61]
	v_pk_fma_f32 v[126:127], v[12:13], v[126:127], v[144:145] op_sel:[1,0,0] op_sel_hi:[0,1,1]
	s_waitcnt lgkmcnt(0)
	v_pk_add_f32 v[58:59], v[140:141], v[146:147]
	ds_swizzle_b32 v140, v138 offset:swizzle(SWAP,4)
	ds_swizzle_b32 v141, v139 offset:swizzle(SWAP,4)
	v_pk_fma_f32 v[144:145], v[14:15], v[154:155], v[152:153] op_sel:[1,0,0] op_sel_hi:[0,1,1]
	v_pk_add_f32 v[126:127], v[126:127], v[144:145]
	v_pk_fma_f32 v[144:145], v[8:9], v[148:149], v[156:157] op_sel:[1,0,0] op_sel_hi:[0,1,1]
	v_pk_mul_f32 v[124:125], v[4:5], v[124:125]
	s_waitcnt lgkmcnt(0)
	v_pk_add_f32 v[138:139], v[138:139], v[140:141]
	ds_swizzle_b32 v140, v138 offset:swizzle(SWAP,8)
	ds_swizzle_b32 v141, v139 offset:swizzle(SWAP,8)
	v_pk_mul_f32 v[120:121], v[6:7], v[120:121]
	v_pk_fma_f32 v[122:123], v[4:5], v[122:123], v[124:125] op_sel:[0,0,1] op_sel_hi:[1,1,0]
	v_pk_fma_f32 v[118:119], v[6:7], v[118:119], v[120:121] op_sel:[0,0,1] op_sel_hi:[1,1,0]
	v_pk_mul_f32 v[114:115], v[0:1], v[114:115]
	s_waitcnt lgkmcnt(0)
	v_pk_add_f32 v[138:139], v[138:139], v[140:141]
	v_pk_mul_f32 v[140:141], v[18:19], v[170:171]
	v_pk_mul_f32 v[110:111], v[2:3], v[110:111]
	v_pk_fma_f32 v[140:141], v[18:19], v[168:169], v[140:141] op_sel:[1,0,0] op_sel_hi:[0,1,1]
	v_pk_add_f32 v[140:141], v[158:159], v[140:141]
	v_pk_add_f32 v[118:119], v[122:123], v[118:119]
	v_pk_add_f32 v[140:141], v[150:151], v[140:141]
	v_pk_fma_f32 v[114:115], v[0:1], v[116:117], v[114:115] op_sel:[1,0,0] op_sel_hi:[0,1,1]
	v_pk_add_f32 v[128:129], v[140:141], v[128:129]
	v_pk_fma_f32 v[110:111], v[2:3], v[112:113], v[110:111] op_sel:[1,0,0] op_sel_hi:[0,1,1]
	v_pk_add_f32 v[128:129], v[128:129], v[142:143]
	v_pk_mul_f32 v[142:143], v[10:11], v[170:171]
	v_pk_add_f32 v[110:111], v[114:115], v[110:111]
	v_pk_fma_f32 v[142:143], v[10:11], v[168:169], v[142:143] op_sel:[1,0,0] op_sel_hi:[0,1,1]
	v_pk_add_f32 v[142:143], v[144:145], v[142:143]
	ds_swizzle_b32 v140, v128 offset:swizzle(SWAP,1)
	v_pk_add_f32 v[126:127], v[126:127], v[142:143]
	ds_swizzle_b32 v141, v129 offset:swizzle(SWAP,1)
	v_pk_add_f32 v[118:119], v[126:127], v[118:119]
	ds_swizzle_b32 v114, v138 offset:swizzle(SWAP,16)
	v_pk_add_f32 v[110:111], v[118:119], v[110:111]
	ds_swizzle_b32 v112, v110 offset:swizzle(SWAP,1)
	ds_swizzle_b32 v113, v111 offset:swizzle(SWAP,1)
	s_waitcnt lgkmcnt(3)
	v_pk_add_f32 v[116:117], v[128:129], v[140:141]
	ds_swizzle_b32 v118, v116 offset:swizzle(SWAP,2)
	ds_swizzle_b32 v119, v117 offset:swizzle(SWAP,2)
	ds_swizzle_b32 v115, v139 offset:swizzle(SWAP,16)
	s_waitcnt lgkmcnt(3)
	v_pk_add_f32 v[110:111], v[110:111], v[112:113]
	ds_swizzle_b32 v112, v110 offset:swizzle(SWAP,2)
	ds_swizzle_b32 v113, v111 offset:swizzle(SWAP,2)
	s_waitcnt lgkmcnt(3)
	v_pk_add_f32 v[116:117], v[116:117], v[118:119]
	ds_swizzle_b32 v118, v116 offset:swizzle(SWAP,4)
	ds_swizzle_b32 v119, v117 offset:swizzle(SWAP,4)
	v_lshlrev_b32_e32 v124, 16, v40
	s_waitcnt lgkmcnt(2)
	v_pk_add_f32 v[112:113], v[110:111], v[112:113]
	ds_swizzle_b32 v120, v112 offset:swizzle(SWAP,4)
	ds_swizzle_b32 v121, v113 offset:swizzle(SWAP,4)
	v_pk_add_f32 v[110:111], v[138:139], v[114:115]
	s_waitcnt lgkmcnt(2)
	v_pk_add_f32 v[114:115], v[116:117], v[118:119]
	v_and_b32_e32 v125, 0xffff0000, v44
	v_pk_mul_f32 v[126:127], v[52:53], v[124:125]
	s_waitcnt lgkmcnt(0)
	v_pk_add_f32 v[112:113], v[112:113], v[120:121]
	ds_swizzle_b32 v118, v112 offset:swizzle(SWAP,8)
	ds_swizzle_b32 v119, v113 offset:swizzle(SWAP,8)
	ds_swizzle_b32 v60, v58 offset:swizzle(SWAP,8)
	ds_swizzle_b32 v61, v59 offset:swizzle(SWAP,8)
	ds_swizzle_b32 v116, v114 offset:swizzle(SWAP,8)
	ds_swizzle_b32 v117, v115 offset:swizzle(SWAP,8)
	s_waitcnt lgkmcnt(4)
	v_pk_add_f32 v[112:113], v[112:113], v[118:119]
	ds_swizzle_b32 v122, v112 offset:swizzle(SWAP,16)
	ds_swizzle_b32 v123, v113 offset:swizzle(SWAP,16)
	s_waitcnt lgkmcnt(4)
	v_pk_add_f32 v[58:59], v[58:59], v[60:61]
	s_waitcnt lgkmcnt(2)
	v_pk_add_f32 v[114:115], v[114:115], v[116:117]
	ds_swizzle_b32 v60, v58 offset:swizzle(SWAP,16)
	ds_swizzle_b32 v61, v59 offset:swizzle(SWAP,16)
	s_waitcnt lgkmcnt(2)
	v_pk_add_f32 v[112:113], v[112:113], v[122:123]
	v_and_b32_e32 v122, 0xffff0000, v40
	v_lshlrev_b32_e32 v123, 16, v44
	v_pk_fma_f32 v[52:53], v[52:53], v[122:123], v[126:127] op_sel:[1,0,0] op_sel_hi:[0,1,1]
	v_pk_mul_f32 v[126:127], v[48:49], v[124:125]
	v_lshlrev_b32_e32 v40, 16, v41
	v_pk_fma_f32 v[48:49], v[48:49], v[122:123], v[126:127] op_sel:[1,0,0] op_sel_hi:[0,1,1]
	v_pk_mul_f32 v[126:127], v[32:33], v[124:125]
	ds_swizzle_b32 v116, v114 offset:swizzle(SWAP,16)
	v_pk_fma_f32 v[32:33], v[32:33], v[122:123], v[126:127] op_sel:[1,0,0] op_sel_hi:[0,1,1]
	v_pk_mul_f32 v[126:127], v[28:29], v[124:125]
	v_pk_mul_f32 v[124:125], v[12:13], v[124:125]
	v_pk_fma_f32 v[28:29], v[28:29], v[122:123], v[126:127] op_sel:[1,0,0] op_sel_hi:[0,1,1]
	v_and_b32_e32 v126, 0xffff0000, v41
	v_and_b32_e32 v41, 0xffff0000, v45
	v_lshlrev_b32_e32 v127, 16, v45
	v_pk_mul_f32 v[44:45], v[54:55], v[40:41]
	v_pk_fma_f32 v[12:13], v[12:13], v[122:123], v[124:125] op_sel:[1,0,0] op_sel_hi:[0,1,1]
	v_pk_fma_f32 v[44:45], v[54:55], v[126:127], v[44:45] op_sel:[1,0,0] op_sel_hi:[0,1,1]
	v_pk_add_f32 v[44:45], v[52:53], v[44:45]
	v_pk_mul_f32 v[52:53], v[50:51], v[40:41]
	ds_swizzle_b32 v117, v115 offset:swizzle(SWAP,16)
	v_pk_fma_f32 v[50:51], v[50:51], v[126:127], v[52:53] op_sel:[1,0,0] op_sel_hi:[0,1,1]
	v_lshlrev_b32_e32 v52, 16, v42
	v_and_b32_e32 v53, 0xffff0000, v46
	v_pk_add_f32 v[48:49], v[48:49], v[50:51]
	v_and_b32_e32 v50, 0xffff0000, v42
	v_lshlrev_b32_e32 v51, 16, v46
	v_pk_mul_f32 v[54:55], v[36:37], v[52:53]
	v_lshlrev_b32_e32 v42, 16, v43
	v_pk_fma_f32 v[36:37], v[36:37], v[50:51], v[54:55] op_sel:[1,0,0] op_sel_hi:[0,1,1]
	v_and_b32_e32 v54, 0xffff0000, v43
	v_and_b32_e32 v43, 0xffff0000, v47
	v_lshlrev_b32_e32 v55, 16, v47
	v_pk_mul_f32 v[46:47], v[38:39], v[42:43]
	s_waitcnt lgkmcnt(2)
	v_pk_add_f32 v[58:59], v[58:59], v[60:61]
	v_pk_fma_f32 v[38:39], v[38:39], v[54:55], v[46:47] op_sel:[1,0,0] op_sel_hi:[0,1,1]
	v_pk_add_f32 v[36:37], v[36:37], v[38:39]
	s_waitcnt lgkmcnt(0)
	v_pk_add_f32 v[116:117], v[114:115], v[116:117]
	v_pk_add_f32 v[36:37], v[44:45], v[36:37]
	v_pk_mul_f32 v[44:45], v[34:35], v[40:41]
	v_pk_add_f32 v[36:37], v[36:37], v[106:107]
	v_pk_fma_f32 v[34:35], v[34:35], v[126:127], v[44:45] op_sel:[1,0,0] op_sel_hi:[0,1,1]
	v_pk_add_f32 v[36:37], v[36:37], v[108:109]
	ds_swizzle_b32 v38, v36 offset:swizzle(SWAP,1)
	ds_swizzle_b32 v39, v37 offset:swizzle(SWAP,1)
	v_pk_add_f32 v[32:33], v[32:33], v[34:35]
	v_pk_mul_f32 v[34:35], v[30:31], v[40:41]
	ds_bpermute_b32 v62, v132, v56
	v_pk_fma_f32 v[30:31], v[30:31], v[126:127], v[34:35] op_sel:[1,0,0] op_sel_hi:[0,1,1]
	s_waitcnt lgkmcnt(1)
	v_pk_add_f32 v[36:37], v[36:37], v[38:39]
	ds_swizzle_b32 v38, v36 offset:swizzle(SWAP,2)
	ds_swizzle_b32 v39, v37 offset:swizzle(SWAP,2)
	v_pk_add_f32 v[28:29], v[28:29], v[30:31]
	v_pk_mul_f32 v[30:31], v[14:15], v[40:41]
	v_pk_mul_f32 v[34:35], v[24:25], v[52:53]
	v_pk_mul_f32 v[40:41], v[26:27], v[42:43]
	s_waitcnt lgkmcnt(0)
	v_pk_add_f32 v[36:37], v[36:37], v[38:39]
	ds_swizzle_b32 v38, v36 offset:swizzle(SWAP,4)
	ds_swizzle_b32 v39, v37 offset:swizzle(SWAP,4)
	v_pk_fma_f32 v[24:25], v[24:25], v[50:51], v[34:35] op_sel:[1,0,0] op_sel_hi:[0,1,1]
	v_pk_fma_f32 v[26:27], v[26:27], v[54:55], v[40:41] op_sel:[1,0,0] op_sel_hi:[0,1,1]
	v_pk_add_f32 v[24:25], v[24:25], v[26:27]
	v_pk_mul_f32 v[34:35], v[20:21], v[52:53]
	v_pk_add_f32 v[24:25], v[48:49], v[24:25]
	s_waitcnt lgkmcnt(0)
	v_pk_add_f32 v[36:37], v[36:37], v[38:39]
	v_pk_add_f32 v[24:25], v[24:25], v[102:103]
	ds_swizzle_b32 v38, v36 offset:swizzle(SWAP,8)
	v_pk_add_f32 v[24:25], v[24:25], v[104:105]
	ds_swizzle_b32 v26, v24 offset:swizzle(SWAP,1)
	ds_swizzle_b32 v27, v25 offset:swizzle(SWAP,1)
	ds_swizzle_b32 v39, v37 offset:swizzle(SWAP,8)
	v_pk_fma_f32 v[20:21], v[20:21], v[50:51], v[34:35] op_sel:[1,0,0] op_sel_hi:[0,1,1]
	v_pk_mul_f32 v[34:35], v[16:17], v[52:53]
	v_pk_mul_f32 v[40:41], v[8:9], v[52:53]
	s_waitcnt lgkmcnt(1)
	v_pk_add_f32 v[24:25], v[24:25], v[26:27]
	v_pk_fma_f32 v[34:35], v[16:17], v[50:51], v[34:35] op_sel:[1,0,0] op_sel_hi:[0,1,1]
	s_waitcnt lgkmcnt(0)
	v_pk_add_f32 v[16:17], v[36:37], v[38:39]
	ds_swizzle_b32 v26, v24 offset:swizzle(SWAP,2)
	ds_swizzle_b32 v27, v25 offset:swizzle(SWAP,2)
	v_pk_mul_f32 v[38:39], v[22:23], v[42:43]
	ds_swizzle_b32 v36, v16 offset:swizzle(SWAP,16)
	v_pk_fma_f32 v[22:23], v[22:23], v[54:55], v[38:39] op_sel:[1,0,0] op_sel_hi:[0,1,1]
	v_pk_add_f32 v[20:21], v[20:21], v[22:23]
	s_waitcnt lgkmcnt(1)
	v_pk_add_f32 v[24:25], v[24:25], v[26:27]
	v_pk_add_f32 v[20:21], v[32:33], v[20:21]
	ds_swizzle_b32 v26, v24 offset:swizzle(SWAP,4)
	v_pk_add_f32 v[20:21], v[20:21], v[98:99]
	ds_swizzle_b32 v27, v25 offset:swizzle(SWAP,4)
	v_pk_add_f32 v[20:21], v[20:21], v[100:101]
	ds_swizzle_b32 v22, v20 offset:swizzle(SWAP,1)
	ds_swizzle_b32 v23, v21 offset:swizzle(SWAP,1)
	ds_swizzle_b32 v37, v17 offset:swizzle(SWAP,16)
	s_waitcnt lgkmcnt(3)
	v_pk_add_f32 v[26:27], v[24:25], v[26:27]
	ds_swizzle_b32 v32, v26 offset:swizzle(SWAP,8)
	ds_swizzle_b32 v33, v27 offset:swizzle(SWAP,8)
	s_waitcnt lgkmcnt(3)
	v_pk_add_f32 v[20:21], v[20:21], v[22:23]
	ds_swizzle_b32 v22, v20 offset:swizzle(SWAP,2)
	ds_swizzle_b32 v23, v21 offset:swizzle(SWAP,2)
	s_waitcnt lgkmcnt(4)
	v_pk_add_f32 v[16:17], v[16:17], v[36:37]
	s_waitcnt lgkmcnt(2)
	v_pk_add_f32 v[26:27], v[26:27], v[32:33]
	ds_swizzle_b32 v32, v26 offset:swizzle(SWAP,16)
	ds_swizzle_b32 v33, v27 offset:swizzle(SWAP,16)
	s_waitcnt lgkmcnt(2)
	v_pk_add_f32 v[20:21], v[20:21], v[22:23]
	ds_swizzle_b32 v22, v20 offset:swizzle(SWAP,4)
	ds_swizzle_b32 v23, v21 offset:swizzle(SWAP,4)
	v_pk_fma_f32 v[8:9], v[8:9], v[50:51], v[40:41] op_sel:[1,0,0] op_sel_hi:[0,1,1]
	v_pk_fma_f32 v[14:15], v[14:15], v[126:127], v[30:31] op_sel:[1,0,0] op_sel_hi:[0,1,1]
	v_pk_add_f32 v[12:13], v[12:13], v[14:15]
	ds_bpermute_b32 v63, v132, v57
	s_waitcnt lgkmcnt(1)
	v_pk_add_f32 v[36:37], v[20:21], v[22:23]
	v_pk_add_f32 v[20:21], v[26:27], v[32:33]
	v_pk_mul_f32 v[32:33], v[18:19], v[42:43]
	ds_swizzle_b32 v38, v36 offset:swizzle(SWAP,8)
	v_pk_fma_f32 v[18:19], v[18:19], v[54:55], v[32:33] op_sel:[1,0,0] op_sel_hi:[0,1,1]
	v_pk_mul_f32 v[32:33], v[10:11], v[42:43]
	v_pk_add_f32 v[18:19], v[34:35], v[18:19]
	v_pk_fma_f32 v[10:11], v[10:11], v[54:55], v[32:33] op_sel:[1,0,0] op_sel_hi:[0,1,1]
	v_pk_add_f32 v[8:9], v[8:9], v[10:11]
	v_pk_mul_f32 v[10:11], v[4:5], v[92:93]
	v_pk_add_f32 v[18:19], v[28:29], v[18:19]
	v_pk_fma_f32 v[4:5], v[4:5], v[88:89], v[10:11] op_sel:[0,0,1] op_sel_hi:[1,1,0]
	v_pk_mul_f32 v[10:11], v[6:7], v[90:91]
	v_pk_add_f32 v[8:9], v[12:13], v[8:9]
	v_pk_fma_f32 v[6:7], v[6:7], v[86:87], v[10:11] op_sel:[0,0,1] op_sel_hi:[1,1,0]
	v_pk_add_f32 v[18:19], v[18:19], v[94:95]
	v_pk_add_f32 v[4:5], v[4:5], v[6:7]
	v_pk_mul_f32 v[6:7], v[0:1], v[82:83]
	v_pk_add_f32 v[4:5], v[8:9], v[4:5]
	v_pk_fma_f32 v[0:1], v[0:1], v[84:85], v[6:7] op_sel:[1,0,0] op_sel_hi:[0,1,1]
	v_pk_mul_f32 v[6:7], v[2:3], v[78:79]
	v_pk_add_f32 v[18:19], v[18:19], v[96:97]
	v_pk_fma_f32 v[2:3], v[2:3], v[80:81], v[6:7] op_sel:[1,0,0] op_sel_hi:[0,1,1]
	v_pk_add_f32 v[0:1], v[0:1], v[2:3]
	ds_swizzle_b32 v28, v18 offset:swizzle(SWAP,1)
	v_pk_add_f32 v[0:1], v[4:5], v[0:1]
	ds_swizzle_b32 v29, v19 offset:swizzle(SWAP,1)
	ds_swizzle_b32 v2, v0 offset:swizzle(SWAP,1)
	ds_swizzle_b32 v3, v1 offset:swizzle(SWAP,1)
	ds_swizzle_b32 v39, v37 offset:swizzle(SWAP,8)
	ds_bpermute_b32 v60, v132, v58
	s_waitcnt lgkmcnt(4)
	v_pk_add_f32 v[6:7], v[18:19], v[28:29]
	ds_swizzle_b32 v8, v6 offset:swizzle(SWAP,2)
	s_waitcnt lgkmcnt(3)
	v_pk_add_f32 v[0:1], v[0:1], v[2:3]
	ds_swizzle_b32 v9, v7 offset:swizzle(SWAP,2)
	ds_swizzle_b32 v2, v0 offset:swizzle(SWAP,2)
	ds_swizzle_b32 v3, v1 offset:swizzle(SWAP,2)
	s_waitcnt lgkmcnt(5)
	v_pk_add_f32 v[26:27], v[36:37], v[38:39]
	ds_swizzle_b32 v4, v26 offset:swizzle(SWAP,16)
	s_waitcnt lgkmcnt(3)
	v_pk_add_f32 v[6:7], v[6:7], v[8:9]
	ds_swizzle_b32 v5, v27 offset:swizzle(SWAP,16)
	s_waitcnt lgkmcnt(2)
	v_pk_add_f32 v[2:3], v[0:1], v[2:3]
	ds_swizzle_b32 v8, v6 offset:swizzle(SWAP,4)
	ds_swizzle_b32 v9, v7 offset:swizzle(SWAP,4)
	ds_swizzle_b32 v10, v2 offset:swizzle(SWAP,4)
	ds_swizzle_b32 v11, v3 offset:swizzle(SWAP,4)
	s_waitcnt lgkmcnt(4)
	v_pk_add_f32 v[0:1], v[26:27], v[4:5]
	ds_bpermute_b32 v61, v132, v59
	s_waitcnt lgkmcnt(3)
	v_pk_add_f32 v[4:5], v[6:7], v[8:9]
	ds_swizzle_b32 v6, v4 offset:swizzle(SWAP,8)
	s_waitcnt lgkmcnt(2)
	v_pk_add_f32 v[2:3], v[2:3], v[10:11]
	ds_swizzle_b32 v7, v5 offset:swizzle(SWAP,8)
	ds_swizzle_b32 v8, v2 offset:swizzle(SWAP,8)
	ds_swizzle_b32 v9, v3 offset:swizzle(SWAP,8)
	ds_bpermute_b32 v120, v132, v110
	ds_bpermute_b32 v121, v132, v111
	s_waitcnt lgkmcnt(4)
	v_pk_add_f32 v[4:5], v[4:5], v[6:7]
	ds_swizzle_b32 v6, v4 offset:swizzle(SWAP,16)
	s_waitcnt lgkmcnt(3)
	v_pk_add_f32 v[2:3], v[2:3], v[8:9]
	ds_swizzle_b32 v7, v5 offset:swizzle(SWAP,16)
	ds_swizzle_b32 v12, v2 offset:swizzle(SWAP,16)
	ds_swizzle_b32 v13, v3 offset:swizzle(SWAP,16)
	ds_bpermute_b32 v118, v132, v116
	ds_bpermute_b32 v119, v132, v117
	s_waitcnt lgkmcnt(4)
	v_pk_add_f32 v[6:7], v[4:5], v[6:7]
	ds_bpermute_b32 v114, v132, v112
	s_waitcnt lgkmcnt(3)
	v_pk_add_f32 v[2:3], v[2:3], v[12:13]
	ds_bpermute_b32 v115, v132, v113
	ds_bpermute_b32 v24, v132, v16
	ds_bpermute_b32 v25, v132, v17
	ds_bpermute_b32 v22, v132, v20
	ds_bpermute_b32 v23, v132, v21
	ds_bpermute_b32 v10, v132, v0
	ds_bpermute_b32 v11, v132, v1
	ds_bpermute_b32 v8, v132, v6
	ds_bpermute_b32 v9, v132, v7
	ds_bpermute_b32 v4, v132, v2
	ds_bpermute_b32 v5, v132, v3
	s_and_saveexec_b64 s[26:27], s[6:7]
	s_cbranch_execz .LBB0_914
	s_add_u32 s28, s8, s14
	s_addc_u32 s29, s9, s15
	s_waitcnt lgkmcnt(8)
	v_pk_add_f32 v[14:15], v[16:17], v[24:25]
	v_pk_add_f32 v[12:13], v[56:57], v[62:63]
	global_store_dwordx4 v65, v[12:15], s[28:29] offset:2048
	s_waitcnt lgkmcnt(2)
	v_pk_add_f32 v[8:9], v[6:7], v[8:9]
	v_pk_add_f32 v[6:7], v[116:117], v[118:119]
	v_pk_add_f32 v[14:15], v[20:21], v[22:23]
	v_pk_add_f32 v[12:13], v[58:59], v[60:61]
	global_store_dwordx4 v133, v[12:15], s[28:29] offset:2048
	s_waitcnt lgkmcnt(0)
	v_pk_add_f32 v[2:3], v[2:3], v[4:5]
	global_store_dwordx4 v135, v[6:9], s[28:29] offset:2048
	v_pk_add_f32 v[12:13], v[0:1], v[10:11]
	v_pk_add_f32 v[10:11], v[110:111], v[120:121]
	v_pk_add_f32 v[0:1], v[112:113], v[114:115]
	global_store_dwordx4 v134, v[10:13], s[28:29] offset:2048
	global_store_dwordx4 v136, v[0:3], s[28:29] offset:2048
	s_branch .LBB0_914
.Lb1_done:
	s_mov_b32 s0, 0
	s_and_b64 vcc, exec, s[76:77]
	s_waitcnt lgkmcnt(0)
	s_mov_b64 s[8:9], 0
	s_cbranch_vccnz .LBB0_614
	v_mbcnt_lo_u32_b32 v0, -1, s0
	v_mbcnt_hi_u32_b32 v0, -1, v0
	v_cmp_eq_u32_e32 vcc, 0, v0
	s_and_b64 s[8:9], vcc, exec

.LBB0_911:
	s_load_dwordx2 s[8:9], s[82:83], 0xb0
	s_cmp_lt_i32 s93, 0
	s_cbranch_scc1 .LBB0_922
	v_mbcnt_lo_u32_b32 v0, -1, s0
	v_mbcnt_hi_u32_b32 v130, -1, v0
	s_lshl_b32 s10, s90, 2
	v_lshlrev_b32_e32 v64, 4, v130
	v_lshlrev_b32_e32 v131, 2, v130
	v_cmp_eq_u32_e64 s[6:7], 0, v130
